# adds: sample-MLA flash loop caches its 10 per-lane staging addresses (captured on passes 1-2, advanced by per-lane delta for pairs 3-15) instead of recomputing ~770 instructions per iteration
# speedup vs baseline: 1.0017x; 1.0017x over previous
; __device__ __forceinline__ void mla_sample_unit(LAS unsigned char* lds, size_t ws_q, size_t ws_olat, size_t ws_mixed, int b) {
;     ...
;         if (2 * pi + 2 < AS_NT) AS_GLOAD(pi + 1);
.LBB0_751:
	s_cmp_lg_u32 s14, 34
	v_and_b32_e32 v1, 15, v180
	v_lshrrev_b32_e32 v2, 2, v180
	s_cselect_b64 s[8:9], -1, 0
	s_cmp_eq_u32 s14, 34
	v_lshrrev_b32_e32 v185, 4, v180
	v_bfe_u32 v6, v180, 4, 2
	v_cmp_lt_i32_e32 vcc, s0, v180
	v_and_or_b32 v184, v2, 48, v1
	s_cbranch_scc1 .LBB0_893
	s_cmp_lt_u32 s14, 6
	s_cbranch_scc1 .Lmf_orig
	s_cmp_gt_u32 s14, 30
	s_cbranch_scc1 .Lmf_orig
	s_waitcnt vmcnt(0)
	v_lshl_add_u64 v[206:207], v[206:207], 0, v[226:227]
	global_load_dwordx4 v[112:115], v[206:207], off
	v_lshl_add_u64 v[208:209], v[208:209], 0, v[228:229]
	global_load_dwordx4 v[116:119], v[208:209], off
	v_lshl_add_u64 v[210:211], v[210:211], 0, v[230:231]
	global_load_dwordx4 v[120:123], v[210:211], off
	v_lshl_add_u64 v[212:213], v[212:213], 0, v[232:233]
	global_load_dwordx4 v[124:127], v[212:213], off
	v_lshl_add_u64 v[214:215], v[214:215], 0, v[234:235]
	global_load_dwordx4 v[128:131], v[214:215], off
	v_lshl_add_u64 v[216:217], v[216:217], 0, v[236:237]
	global_load_dwordx4 v[132:135], v[216:217], off
	v_lshl_add_u64 v[218:219], v[218:219], 0, v[238:239]
	global_load_dwordx4 v[136:139], v[218:219], off
	v_lshl_add_u64 v[220:221], v[220:221], 0, v[240:241]
	global_load_dwordx4 v[140:143], v[220:221], off
	v_lshl_add_u64 v[222:223], v[222:223], 0, v[242:243]
	global_load_dwordx4 v[144:147], v[222:223], off
	v_lshl_add_u64 v[224:225], v[224:225], 0, v[244:245]
	global_load_dwordx4 v[148:151], v[224:225], off
	s_branch .LBB0_893
.Lmf_orig:
	v_cndmask_b32_e32 v1, 0, v172, vcc
	v_add_u32_e32 v1, v1, v180
	v_ashrrev_i32_e32 v1, 6, v1
	s_cmp_gt_u32 s15, 14
	v_bfi_b32 v2, -4, v1, v185
	v_mov_b32_e32 v1, s14
	s_cselect_b64 s[10:11], -1, 0
	v_addc_co_u32_e32 v1, vcc, 0, v1, vcc
	v_lshl_or_b32 v1, v1, 6, v184
	v_cmp_lt_i32_e64 s[2:3], 31, v2
	v_lshlrev_b32_e32 v2, 2, v2
	s_mov_b64 s[4:5], -1
	s_and_b64 vcc, exec, s[10:11]
	s_cbranch_vccz .LBB0_758
	v_add_u32_e32 v8, s48, v1
	v_ashrrev_i32_e32 v9, 31, v8
	s_and_saveexec_b64 s[4:5], s[2:3]
	s_xor_b64 s[4:5], exec, s[4:5]
	v_lshlrev_b64 v[4:5], 7, v[8:9]
	v_lshl_add_u64 v[4:5], s[64:65], 0, v[4:5]
	v_mov_b32_e32 v3, v0
	v_lshl_add_u64 v[4:5], v[2:3], 2, v[4:5]
	v_lshl_add_u64 v[4:5], v[4:5], 0, s[54:55]
	s_andn2_saveexec_b64 s[4:5], s[4:5]
	v_lshlrev_b64 v[4:5], 9, v[8:9]
	v_ashrrev_i32_e32 v3, 31, v2
	v_lshl_add_u64 v[4:5], s[6:7], 0, v[4:5]
	v_lshl_add_u64 v[4:5], v[2:3], 2, v[4:5]
	s_or_b64 exec, exec, s[4:5]
	s_mov_b64 s[4:5], 0

.LBB0_764:
	v_mov_b32_e32 v2, v0
	v_mov_b32_e32 v3, v0
	v_cmp_gt_u32_e32 vcc, s85, v1
	v_mov_b32_e32 v1, v0
	s_waitcnt vmcnt(0)
	v_mov_b64_e32 v[114:115], v[2:3]
	v_mov_b64_e32 v[112:113], v[0:1]
	s_and_saveexec_b64 s[2:3], vcc
	s_cbranch_execz .LBB0_766
	global_load_dwordx4 v[112:115], v[4:5], off
	v_sub_u32_e32 v226, v4, v206
	v_mov_b32_e32 v227, 0
	v_mov_b64_e32 v[206:207], v[4:5]

.LBB0_778:
	v_mov_b32_e32 v2, v0
	v_mov_b32_e32 v3, v0
	v_cmp_gt_u32_e32 vcc, s85, v1
	v_mov_b32_e32 v1, v0
	v_mov_b64_e32 v[118:119], v[2:3]
	v_mov_b64_e32 v[116:117], v[0:1]
	s_and_saveexec_b64 s[4:5], vcc
	s_cbranch_execz .LBB0_780
	global_load_dwordx4 v[116:119], v[4:5], off
	v_sub_u32_e32 v228, v4, v208
	v_mov_b32_e32 v229, 0
	v_mov_b64_e32 v[208:209], v[4:5]

.LBB0_792:
	v_mov_b32_e32 v2, v0
	v_mov_b32_e32 v3, v0
	v_cmp_gt_u32_e32 vcc, s85, v1
	v_mov_b32_e32 v1, v0
	v_mov_b64_e32 v[122:123], v[2:3]
	v_mov_b64_e32 v[120:121], v[0:1]
	s_and_saveexec_b64 s[4:5], vcc
	s_cbranch_execz .LBB0_794
	global_load_dwordx4 v[120:123], v[4:5], off
	v_sub_u32_e32 v230, v4, v210
	v_mov_b32_e32 v231, 0
	v_mov_b64_e32 v[210:211], v[4:5]

.LBB0_806:
	v_mov_b32_e32 v2, v0
	v_mov_b32_e32 v3, v0
	v_cmp_gt_u32_e32 vcc, s85, v1
	v_mov_b32_e32 v1, v0
	v_mov_b64_e32 v[126:127], v[2:3]
	v_mov_b64_e32 v[124:125], v[0:1]
	s_and_saveexec_b64 s[4:5], vcc
	s_cbranch_execz .LBB0_808
	global_load_dwordx4 v[124:127], v[4:5], off
	v_sub_u32_e32 v232, v4, v212
	v_mov_b32_e32 v233, 0
	v_mov_b64_e32 v[212:213], v[4:5]

.LBB0_820:
	v_mov_b32_e32 v2, v0
	v_mov_b32_e32 v3, v0
	v_cmp_gt_u32_e32 vcc, s85, v1
	v_mov_b32_e32 v1, v0
	v_mov_b64_e32 v[130:131], v[2:3]
	v_mov_b64_e32 v[128:129], v[0:1]
	s_and_saveexec_b64 s[4:5], vcc
	s_cbranch_execz .LBB0_822
	global_load_dwordx4 v[128:131], v[4:5], off
	v_sub_u32_e32 v234, v4, v214
	v_mov_b32_e32 v235, 0
	v_mov_b64_e32 v[214:215], v[4:5]

.LBB0_834:
	v_mov_b32_e32 v2, v0
	v_mov_b32_e32 v3, v0
	v_cmp_gt_u32_e32 vcc, s85, v1
	v_mov_b32_e32 v1, v0
	v_mov_b64_e32 v[134:135], v[2:3]
	v_mov_b64_e32 v[132:133], v[0:1]
	s_and_saveexec_b64 s[4:5], vcc
	s_cbranch_execz .LBB0_836
	global_load_dwordx4 v[132:135], v[4:5], off
	v_sub_u32_e32 v236, v4, v216
	v_mov_b32_e32 v237, 0
	v_mov_b64_e32 v[216:217], v[4:5]

.LBB0_848:
	v_mov_b32_e32 v2, v0
	v_mov_b32_e32 v3, v0
	v_cmp_gt_u32_e32 vcc, s85, v1
	v_mov_b32_e32 v1, v0
	v_mov_b64_e32 v[138:139], v[2:3]
	v_mov_b64_e32 v[136:137], v[0:1]
	s_and_saveexec_b64 s[4:5], vcc
	s_cbranch_execz .LBB0_850
	global_load_dwordx4 v[136:139], v[4:5], off
	v_sub_u32_e32 v238, v4, v218
	v_mov_b32_e32 v239, 0
	v_mov_b64_e32 v[218:219], v[4:5]

.LBB0_862:
	v_mov_b32_e32 v2, v0
	v_mov_b32_e32 v3, v0
	v_cmp_gt_u32_e32 vcc, s85, v1
	v_mov_b32_e32 v1, v0
	v_mov_b64_e32 v[142:143], v[2:3]
	v_mov_b64_e32 v[140:141], v[0:1]
	s_and_saveexec_b64 s[4:5], vcc
	s_cbranch_execz .LBB0_864
	global_load_dwordx4 v[140:143], v[4:5], off
	v_sub_u32_e32 v240, v4, v220
	v_mov_b32_e32 v241, 0
	v_mov_b64_e32 v[220:221], v[4:5]

.LBB0_876:
	v_mov_b32_e32 v2, v0
	v_mov_b32_e32 v3, v0
	v_cmp_gt_u32_e32 vcc, s85, v1
	v_mov_b32_e32 v1, v0
	v_mov_b64_e32 v[146:147], v[2:3]
	v_mov_b64_e32 v[144:145], v[0:1]
	s_and_saveexec_b64 s[4:5], vcc
	s_cbranch_execz .LBB0_878
	global_load_dwordx4 v[144:147], v[4:5], off
	v_sub_u32_e32 v242, v4, v222
	v_mov_b32_e32 v243, 0
	v_mov_b64_e32 v[222:223], v[4:5]

.LBB0_890:
	v_mov_b32_e32 v2, v0
	v_mov_b32_e32 v3, v0
	v_cmp_gt_u32_e32 vcc, s85, v1
	v_mov_b32_e32 v1, v0
	v_mov_b64_e32 v[150:151], v[2:3]
	v_mov_b64_e32 v[148:149], v[0:1]
	s_and_saveexec_b64 s[2:3], vcc
	s_cbranch_execz .LBB0_892
	global_load_dwordx4 v[148:151], v[4:5], off
	v_sub_u32_e32 v244, v4, v224
	v_mov_b32_e32 v245, 0
	v_mov_b64_e32 v[224:225], v[4:5]
